# P8 HID stores with nt cache policy
# speedup vs baseline: 1.0024x; 1.0024x over previous
.LBB0_877:
	s_cmp_eq_u32 s100, 0
	s_cbranch_scc1 .Ldhs8_idle
	s_cmp_lt_i32 s61, 6
	s_cbranch_scc0 .Ldhs8_hi
	s_cmp_lt_i32 s61, 2
	s_cbranch_scc0 .Ldhs8_q1
	s_cmp_lt_i32 s61, 0
	s_cbranch_scc0 .Ldhs8_g9
	global_store_dwordx4 v255, v[226:229], s[16:17] nt
	s_branch .Ldhs8_done
.Ldhs8_g9:
	global_store_dwordx4 v255, v[230:233], s[18:19] nt
	s_branch .Ldhs8_done
.Ldhs8_q1:
	s_cmp_lt_i32 s61, 4
	s_cbranch_scc0 .Ldhs8_g11
	global_store_dwordx4 v255, v[234:237], s[16:17] offset:1024 nt
	s_branch .Ldhs8_done
.Ldhs8_g11:
	global_store_dwordx4 v255, v[238:241], s[18:19] offset:1024 nt
	s_branch .Ldhs8_done
.Ldhs8_hi:
	s_cmp_lt_i32 s61, 10
	s_cbranch_scc0 .Ldhs8_q3
	s_cmp_lt_i32 s61, 8
	s_cbranch_scc0 .Ldhs8_g13
	global_store_dwordx4 v255, v[242:245], s[16:17] offset:2048 nt
	s_branch .Ldhs8_done
.Ldhs8_g13:
	global_store_dwordx4 v255, v[246:249], s[18:19] offset:2048 nt
	s_branch .Ldhs8_done
.Ldhs8_q3:
	s_cmp_lt_i32 s61, 12
	s_cbranch_scc0 .Ldhs8_g15
	global_store_dwordx4 v255, v[250:253], s[16:17] offset:3072 nt
	s_branch .Ldhs8_done
.Ldhs8_g15:
	global_store_dwordx4 v255, v[140:143], s[18:19] offset:3072 nt
	s_branch .Ldhs8_done

.LBB0_880:
	v_lshl_add_u32 v150, s34, 8, v144
	v_lshl_or_b32 v152, s56, 8, v146
	v_ashrrev_i32_e32 v151, 31, v150
	v_max_f32_e32 v124, 0, v124
	v_max_f32_e32 v120, 0, v120
	v_max_f32_e32 v125, 0, v125
	v_max_f32_e32 v121, 0, v121
	v_max_f32_e32 v126, 0, v126
	v_max_f32_e32 v127, 0, v127
	v_ashrrev_i32_e32 v153, 31, v152
	v_lshlrev_b64 v[154:155], 6, v[150:151]
	v_pk_mul_f32 v[124:125], v[124:125], v[124:125]
	v_pk_mul_f32 v[120:121], v[120:121], v[120:121]
	v_max_f32_e32 v122, 0, v122
	v_max_f32_e32 v123, 0, v123
	v_pk_mul_f32 v[126:127], v[126:127], v[126:127]
	v_pk_mul_f32 v[156:157], v[122:123], v[122:123]
	v_cvt_pk_bf16_f32 v122, v124, v125
	v_cvt_pk_bf16_f32 v123, v126, v127
	v_cvt_pk_bf16_f32 v124, v120, v121
	v_lshl_add_u64 v[120:121], s[78:79], 0, v[154:155]
	v_and_b32_e32 v126, 0xfe0, v152
	v_and_b32_e32 v127, 31, v152
	v_lshlrev_b32_e32 v126, 16, v126
	v_lshl_or_b32 v126, v127, 1, v126
	v_add_u32_e32 v255, v154, v126
	v_mov_b32_e32 v127, 0
	v_cvt_pk_bf16_f32 v125, v156, v157
	v_lshl_add_u64 v[120:121], v[120:121], 0, v[126:127]
	v_max_f32_e32 v112, 0, v112
	v_max_f32_e32 v113, 0, v113
	global_store_dwordx4 v[120:121], v[122:125], off nt
	s_nop 1
	v_pk_mul_f32 v[122:123], v[112:113], v[112:113]
	v_max_f32_e32 v114, 0, v114
	v_max_f32_e32 v116, 0, v116
	v_max_f32_e32 v117, 0, v117
	v_max_f32_e32 v112, 0, v118
	v_max_f32_e32 v113, 0, v119
	v_max_f32_e32 v115, 0, v115
	v_pk_mul_f32 v[116:117], v[116:117], v[116:117]
	v_pk_mul_f32 v[118:119], v[112:113], v[112:113]
	v_pk_mul_f32 v[124:125], v[114:115], v[114:115]
	v_cvt_pk_bf16_f32 v112, v116, v117
	v_cvt_pk_bf16_f32 v113, v118, v119
	v_cvt_pk_bf16_f32 v114, v122, v123
	v_cvt_pk_bf16_f32 v115, v124, v125
	v_max_f32_e32 v104, 0, v104
	v_max_f32_e32 v105, 0, v105
	v_lshl_add_u64 v[200:201], v[120:121], 0, s[98:99]
	global_store_dwordx4 v[200:201], v[112:115], off nt
	s_nop 1
	v_or_b32_e32 v112, 16, v150
	v_pk_mul_f32 v[114:115], v[104:105], v[104:105]
	v_ashrrev_i32_e32 v113, 31, v112
	v_max_f32_e32 v108, 0, v108
	v_max_f32_e32 v109, 0, v109
	v_max_f32_e32 v106, 0, v106
	v_lshlrev_b64 v[112:113], 6, v[112:113]
	v_pk_mul_f32 v[108:109], v[108:109], v[108:109]
	v_max_f32_e32 v104, 0, v110
	v_max_f32_e32 v105, 0, v111
	v_max_f32_e32 v107, 0, v107
	v_pk_mul_f32 v[110:111], v[104:105], v[104:105]
	v_pk_mul_f32 v[116:117], v[106:107], v[106:107]
	v_cvt_pk_bf16_f32 v104, v108, v109
	v_lshl_add_u64 v[108:109], s[78:79], 0, v[112:113]
	v_cvt_pk_bf16_f32 v105, v110, v111
	v_cvt_pk_bf16_f32 v106, v114, v115
	v_cvt_pk_bf16_f32 v107, v116, v117
	v_lshl_add_u64 v[108:109], v[108:109], 0, v[126:127]
	v_max_f32_e32 v96, 0, v96
	v_max_f32_e32 v97, 0, v97
	global_store_dwordx4 v[108:109], v[104:107], off nt
	s_nop 1
	v_pk_mul_f32 v[104:105], v[96:97], v[96:97]
	v_max_f32_e32 v98, 0, v98
	v_max_f32_e32 v100, 0, v100
	v_max_f32_e32 v101, 0, v101
	v_max_f32_e32 v96, 0, v102
	v_max_f32_e32 v97, 0, v103
	v_max_f32_e32 v99, 0, v99
	v_pk_mul_f32 v[100:101], v[100:101], v[100:101]
	v_pk_mul_f32 v[102:103], v[96:97], v[96:97]
	v_pk_mul_f32 v[106:107], v[98:99], v[98:99]
	v_cvt_pk_bf16_f32 v96, v100, v101
	v_cvt_pk_bf16_f32 v97, v102, v103
	v_cvt_pk_bf16_f32 v98, v104, v105
	v_cvt_pk_bf16_f32 v99, v106, v107
	v_max_f32_e32 v88, 0, v88
	v_max_f32_e32 v89, 0, v89
	v_lshl_add_u64 v[202:203], v[108:109], 0, s[98:99]
	global_store_dwordx4 v[202:203], v[96:99], off nt
	s_nop 1
	v_or_b32_e32 v96, 32, v150
	v_pk_mul_f32 v[98:99], v[88:89], v[88:89]
	v_ashrrev_i32_e32 v97, 31, v96
	v_max_f32_e32 v92, 0, v92
	v_max_f32_e32 v93, 0, v93
	v_max_f32_e32 v90, 0, v90
	v_lshlrev_b64 v[96:97], 6, v[96:97]
	v_pk_mul_f32 v[92:93], v[92:93], v[92:93]
	v_max_f32_e32 v88, 0, v94
	v_max_f32_e32 v89, 0, v95
	v_max_f32_e32 v91, 0, v91
	v_pk_mul_f32 v[94:95], v[88:89], v[88:89]
	v_pk_mul_f32 v[100:101], v[90:91], v[90:91]
	v_cvt_pk_bf16_f32 v88, v92, v93
	v_lshl_add_u64 v[92:93], s[78:79], 0, v[96:97]
	v_cvt_pk_bf16_f32 v89, v94, v95
	v_cvt_pk_bf16_f32 v90, v98, v99
	v_cvt_pk_bf16_f32 v91, v100, v101
	v_lshl_add_u64 v[92:93], v[92:93], 0, v[126:127]
	v_max_f32_e32 v80, 0, v80
	v_max_f32_e32 v81, 0, v81
	global_store_dwordx4 v[92:93], v[88:91], off nt
	s_nop 1
	v_pk_mul_f32 v[88:89], v[80:81], v[80:81]
	v_max_f32_e32 v82, 0, v82
	v_max_f32_e32 v84, 0, v84
	v_max_f32_e32 v85, 0, v85
	v_max_f32_e32 v80, 0, v86
	v_max_f32_e32 v81, 0, v87
	v_max_f32_e32 v83, 0, v83
	v_pk_mul_f32 v[84:85], v[84:85], v[84:85]
	v_pk_mul_f32 v[86:87], v[80:81], v[80:81]
	v_pk_mul_f32 v[90:91], v[82:83], v[82:83]
	v_cvt_pk_bf16_f32 v80, v84, v85
	v_cvt_pk_bf16_f32 v81, v86, v87
	v_cvt_pk_bf16_f32 v82, v88, v89
	v_cvt_pk_bf16_f32 v83, v90, v91
	v_max_f32_e32 v72, 0, v72
	v_max_f32_e32 v73, 0, v73
	v_lshl_add_u64 v[204:205], v[92:93], 0, s[98:99]
	global_store_dwordx4 v[204:205], v[80:83], off nt
	s_nop 1
	v_or_b32_e32 v80, 48, v150
	v_pk_mul_f32 v[82:83], v[72:73], v[72:73]
	v_ashrrev_i32_e32 v81, 31, v80
	v_max_f32_e32 v76, 0, v76
	v_max_f32_e32 v77, 0, v77
	v_max_f32_e32 v74, 0, v74
	v_lshlrev_b64 v[80:81], 6, v[80:81]
	v_pk_mul_f32 v[76:77], v[76:77], v[76:77]
	v_max_f32_e32 v72, 0, v78
	v_max_f32_e32 v73, 0, v79
	v_max_f32_e32 v75, 0, v75
	v_pk_mul_f32 v[78:79], v[72:73], v[72:73]
	v_pk_mul_f32 v[84:85], v[74:75], v[74:75]
	v_cvt_pk_bf16_f32 v72, v76, v77
	v_lshl_add_u64 v[76:77], s[78:79], 0, v[80:81]
	v_cvt_pk_bf16_f32 v73, v78, v79
	v_cvt_pk_bf16_f32 v74, v82, v83
	v_cvt_pk_bf16_f32 v75, v84, v85
	v_lshl_add_u64 v[76:77], v[76:77], 0, v[126:127]
	v_max_f32_e32 v64, 0, v64
	v_max_f32_e32 v65, 0, v65
	global_store_dwordx4 v[76:77], v[72:75], off nt
	s_nop 1
	v_pk_mul_f32 v[72:73], v[64:65], v[64:65]
	v_max_f32_e32 v66, 0, v66
	v_max_f32_e32 v68, 0, v68
	v_max_f32_e32 v69, 0, v69
	v_max_f32_e32 v64, 0, v70
	v_max_f32_e32 v65, 0, v71
	v_max_f32_e32 v67, 0, v67
	v_pk_mul_f32 v[68:69], v[68:69], v[68:69]
	v_pk_mul_f32 v[70:71], v[64:65], v[64:65]
	v_pk_mul_f32 v[74:75], v[66:67], v[66:67]
	v_cvt_pk_bf16_f32 v64, v68, v69
	v_cvt_pk_bf16_f32 v65, v70, v71
	v_cvt_pk_bf16_f32 v66, v72, v73
	v_cvt_pk_bf16_f32 v67, v74, v75
	v_max_f32_e32 v56, 0, v56
	v_max_f32_e32 v57, 0, v57
	v_lshl_add_u64 v[206:207], v[76:77], 0, s[98:99]
	global_store_dwordx4 v[206:207], v[64:67], off nt
	s_nop 1
	v_pk_mul_f32 v[64:65], v[56:57], v[56:57]
	v_max_f32_e32 v58, 0, v58
	v_max_f32_e32 v56, 0, v62
	v_max_f32_e32 v57, 0, v63
	v_max_f32_e32 v60, 0, v60
	v_max_f32_e32 v61, 0, v61
	v_max_f32_e32 v59, 0, v59
	v_pk_mul_f32 v[62:63], v[56:57], v[56:57]
	v_pk_mul_f32 v[60:61], v[60:61], v[60:61]
	v_pk_mul_f32 v[66:67], v[58:59], v[58:59]
	v_cvt_pk_bf16_f32 v227, v62, v63
	v_cvt_pk_bf16_f32 v226, v60, v61
	v_cvt_pk_bf16_f32 v228, v64, v65
	v_cvt_pk_bf16_f32 v229, v66, v67
	v_max_f32_e32 v48, 0, v48
	v_max_f32_e32 v49, 0, v49
	v_pk_mul_f32 v[56:57], v[48:49], v[48:49]
	v_max_f32_e32 v50, 0, v50
	v_max_f32_e32 v52, 0, v52
	v_max_f32_e32 v53, 0, v53
	v_max_f32_e32 v48, 0, v54
	v_max_f32_e32 v49, 0, v55
	v_max_f32_e32 v51, 0, v51
	v_pk_mul_f32 v[52:53], v[52:53], v[52:53]
	v_pk_mul_f32 v[54:55], v[48:49], v[48:49]
	v_pk_mul_f32 v[58:59], v[50:51], v[50:51]
	v_cvt_pk_bf16_f32 v230, v52, v53
	v_cvt_pk_bf16_f32 v231, v54, v55
	v_cvt_pk_bf16_f32 v232, v56, v57
	v_cvt_pk_bf16_f32 v233, v58, v59
	v_max_f32_e32 v40, 0, v40
	v_max_f32_e32 v41, 0, v41
	v_pk_mul_f32 v[48:49], v[40:41], v[40:41]
	v_max_f32_e32 v42, 0, v42
	v_max_f32_e32 v40, 0, v46
	v_max_f32_e32 v41, 0, v47
	v_max_f32_e32 v44, 0, v44
	v_max_f32_e32 v45, 0, v45
	v_max_f32_e32 v43, 0, v43
	v_pk_mul_f32 v[46:47], v[40:41], v[40:41]
	v_pk_mul_f32 v[44:45], v[44:45], v[44:45]
	v_pk_mul_f32 v[50:51], v[42:43], v[42:43]
	v_cvt_pk_bf16_f32 v235, v46, v47
	v_cvt_pk_bf16_f32 v234, v44, v45
	v_cvt_pk_bf16_f32 v236, v48, v49
	v_cvt_pk_bf16_f32 v237, v50, v51
	v_max_f32_e32 v32, 0, v32
	v_max_f32_e32 v33, 0, v33
	v_pk_mul_f32 v[40:41], v[32:33], v[32:33]
	v_max_f32_e32 v34, 0, v34
	v_max_f32_e32 v36, 0, v36
	v_max_f32_e32 v37, 0, v37
	v_max_f32_e32 v32, 0, v38
	v_max_f32_e32 v33, 0, v39
	v_max_f32_e32 v35, 0, v35
	v_pk_mul_f32 v[36:37], v[36:37], v[36:37]
	v_pk_mul_f32 v[38:39], v[32:33], v[32:33]
	v_pk_mul_f32 v[42:43], v[34:35], v[34:35]
	v_cvt_pk_bf16_f32 v238, v36, v37
	v_cvt_pk_bf16_f32 v239, v38, v39
	v_cvt_pk_bf16_f32 v240, v40, v41
	v_cvt_pk_bf16_f32 v241, v42, v43
	v_max_f32_e32 v24, 0, v24
	v_max_f32_e32 v25, 0, v25
	v_pk_mul_f32 v[32:33], v[24:25], v[24:25]
	v_max_f32_e32 v26, 0, v26
	v_max_f32_e32 v24, 0, v30
	v_max_f32_e32 v25, 0, v31
	v_max_f32_e32 v28, 0, v28
	v_max_f32_e32 v29, 0, v29
	v_max_f32_e32 v27, 0, v27
	v_pk_mul_f32 v[30:31], v[24:25], v[24:25]
	v_pk_mul_f32 v[28:29], v[28:29], v[28:29]
	v_pk_mul_f32 v[34:35], v[26:27], v[26:27]
	v_cvt_pk_bf16_f32 v243, v30, v31
	v_cvt_pk_bf16_f32 v242, v28, v29
	v_cvt_pk_bf16_f32 v244, v32, v33
	v_cvt_pk_bf16_f32 v245, v34, v35
	v_max_f32_e32 v16, 0, v16
	v_max_f32_e32 v17, 0, v17
	v_pk_mul_f32 v[24:25], v[16:17], v[16:17]
	v_max_f32_e32 v18, 0, v18
	v_max_f32_e32 v20, 0, v20
	v_max_f32_e32 v21, 0, v21
	v_max_f32_e32 v16, 0, v22
	v_max_f32_e32 v17, 0, v23
	v_max_f32_e32 v19, 0, v19
	v_pk_mul_f32 v[20:21], v[20:21], v[20:21]
	v_pk_mul_f32 v[22:23], v[16:17], v[16:17]
	v_pk_mul_f32 v[26:27], v[18:19], v[18:19]
	v_cvt_pk_bf16_f32 v246, v20, v21
	v_cvt_pk_bf16_f32 v247, v22, v23
	v_cvt_pk_bf16_f32 v248, v24, v25
	v_cvt_pk_bf16_f32 v249, v26, v27
	v_max_f32_e32 v8, 0, v8
	v_max_f32_e32 v9, 0, v9
	v_pk_mul_f32 v[16:17], v[8:9], v[8:9]
	v_max_f32_e32 v10, 0, v10
	v_max_f32_e32 v8, 0, v14
	v_max_f32_e32 v9, 0, v15
	v_max_f32_e32 v12, 0, v12
	v_max_f32_e32 v13, 0, v13
	v_max_f32_e32 v11, 0, v11
	v_pk_mul_f32 v[14:15], v[8:9], v[8:9]
	v_pk_mul_f32 v[12:13], v[12:13], v[12:13]
	v_pk_mul_f32 v[18:19], v[10:11], v[10:11]
	v_cvt_pk_bf16_f32 v251, v14, v15
	v_cvt_pk_bf16_f32 v250, v12, v13
	v_cvt_pk_bf16_f32 v252, v16, v17
	v_cvt_pk_bf16_f32 v253, v18, v19
	v_max_f32_e32 v0, 0, v0
	v_max_f32_e32 v1, 0, v1
	v_pk_mul_f32 v[8:9], v[0:1], v[0:1]
	v_max_f32_e32 v2, 0, v2
	v_max_f32_e32 v4, 0, v4
	v_max_f32_e32 v5, 0, v5
	v_max_f32_e32 v0, 0, v6
	v_max_f32_e32 v1, 0, v7
	v_max_f32_e32 v3, 0, v3
	v_pk_mul_f32 v[4:5], v[4:5], v[4:5]
	v_pk_mul_f32 v[6:7], v[0:1], v[0:1]
	v_pk_mul_f32 v[10:11], v[2:3], v[2:3]
	v_cvt_pk_bf16_f32 v140, v4, v5
	v_cvt_pk_bf16_f32 v141, v6, v7
	v_cvt_pk_bf16_f32 v142, v8, v9
	v_cvt_pk_bf16_f32 v143, v10, v11
	s_andn2_b64 vcc, exec, s[4:5]
	s_mov_b64 s[4:5], -1
	s_mov_b32 s100, 1
	s_cbranch_vccnz .LBB0_869
	s_andn2_b64 vcc, exec, s[6:7]
	s_cbranch_vccnz .LBB0_868
	s_barrier
	s_branch .LBB0_868
.LBB0_883:
	global_store_dwordx4 v255, v[226:229], s[16:17] nt
	global_store_dwordx4 v255, v[230:233], s[18:19] nt
	global_store_dwordx4 v255, v[234:237], s[16:17] offset:1024 nt
	global_store_dwordx4 v255, v[238:241], s[18:19] offset:1024 nt
	global_store_dwordx4 v255, v[242:245], s[16:17] offset:2048 nt
	global_store_dwordx4 v255, v[246:249], s[18:19] offset:2048 nt
	global_store_dwordx4 v255, v[250:253], s[16:17] offset:3072 nt
	global_store_dwordx4 v255, v[140:143], s[18:19] offset:3072 nt
	s_waitcnt vmcnt(0)
	s_barrier
